# combo14 + attention softmax masking: v_bfe_i32 + v_and per element instead of v_and + v_cmp + v_cndmask (96 VALU fewer per tile pair, no VCC)
# speedup vs baseline: 1.0089x; 1.0089x over previous
.LBB0_1624:
	s_nop 6
	v_exp_f32_e32 v66, v66
	s_waitcnt lgkmcnt(0)
	v_lshrrev_b32_e32 v208, v180, v164
	v_bfe_i32 v236, v208, 0, 1
	v_lshrrev_b32_e32 v230, v180, v165
	v_exp_f32_e32 v82, v82
	s_nop 1
	v_and_b32_e32 v164, v66, v236
	v_bfe_i32 v237, v230, 0, 1
	v_exp_f32_e32 v66, v67
	v_exp_f32_e32 v67, v83
	v_and_b32_e32 v165, v82, v237
	v_bfe_i32 v238, v208, 1, 1
	s_nop 1
	v_and_b32_e32 v199, v66, v238
	v_bfe_i32 v239, v230, 1, 1
	v_exp_f32_e32 v66, v68
	v_bfe_i32 v240, v208, 2, 1
	v_and_b32_e32 v200, v67, v239
	v_exp_f32_e32 v67, v84
	v_bfe_i32 v242, v208, 3, 1
	v_and_b32_e32 v201, v66, v240
	v_bfe_i32 v241, v230, 2, 1
	v_exp_f32_e32 v66, v69
	s_nop 0
	v_and_b32_e32 v202, v67, v241
	v_exp_f32_e32 v67, v85
	v_bfe_i32 v244, v208, 8, 1
	v_and_b32_e32 v203, v66, v242
	v_bfe_i32 v243, v230, 3, 1
	v_exp_f32_e32 v66, v70
	s_nop 0
	v_and_b32_e32 v204, v67, v243
	v_exp_f32_e32 v67, v86
	v_bfe_i32 v246, v208, 9, 1
	v_and_b32_e32 v205, v66, v244
	v_bfe_i32 v245, v230, 8, 1
	v_exp_f32_e32 v66, v71
	s_nop 0
	v_and_b32_e32 v206, v67, v245
	v_exp_f32_e32 v67, v87
	v_bfe_i32 v248, v208, 10, 1
	v_and_b32_e32 v207, v66, v246
	v_bfe_i32 v247, v230, 9, 1
	v_exp_f32_e32 v66, v72
	s_nop 0
	v_and_b32_e32 v209, v67, v247
	v_exp_f32_e32 v67, v88
	v_bfe_i32 v250, v208, 11, 1
	v_and_b32_e32 v210, v66, v248
	v_bfe_i32 v249, v230, 10, 1
	v_exp_f32_e32 v66, v73
	s_nop 0
	v_and_b32_e32 v211, v67, v249
	v_exp_f32_e32 v67, v89
	v_bfe_i32 v236, v208, 16, 1
	v_and_b32_e32 v212, v66, v250
	v_bfe_i32 v251, v230, 11, 1
	v_exp_f32_e32 v66, v74
	s_nop 0
	v_and_b32_e32 v213, v67, v251
	v_exp_f32_e32 v67, v90
	v_bfe_i32 v238, v208, 17, 1
	v_and_b32_e32 v214, v66, v236
	v_bfe_i32 v237, v230, 16, 1
	v_exp_f32_e32 v66, v75
	s_nop 0
	v_and_b32_e32 v215, v67, v237
	v_exp_f32_e32 v67, v91
	v_bfe_i32 v240, v208, 18, 1
	v_and_b32_e32 v216, v66, v238
	v_bfe_i32 v239, v230, 17, 1
	v_exp_f32_e32 v66, v76
	s_nop 0
	v_and_b32_e32 v217, v67, v239
	v_exp_f32_e32 v67, v92
	v_bfe_i32 v242, v208, 19, 1
	v_and_b32_e32 v218, v66, v240
	v_bfe_i32 v241, v230, 18, 1
	v_exp_f32_e32 v66, v77
	s_nop 0
	v_and_b32_e32 v219, v67, v241
	v_exp_f32_e32 v67, v93
	v_bfe_i32 v244, v208, 24, 1
	v_and_b32_e32 v220, v66, v242
	v_bfe_i32 v243, v230, 19, 1
	v_exp_f32_e32 v66, v78
	s_nop 0
	v_and_b32_e32 v221, v67, v243
	v_exp_f32_e32 v67, v94
	v_bfe_i32 v246, v208, 25, 1
	v_and_b32_e32 v223, v66, v244
	v_bfe_i32 v245, v230, 24, 1
	v_exp_f32_e32 v66, v79
	s_nop 0
	v_and_b32_e32 v224, v67, v245
	v_exp_f32_e32 v67, v95
	v_bfe_i32 v248, v208, 26, 1
	v_and_b32_e32 v225, v66, v246
	v_bfe_i32 v247, v230, 25, 1
	v_exp_f32_e32 v66, v80
	s_nop 0
	v_and_b32_e32 v226, v67, v247
	v_exp_f32_e32 v67, v96
	v_bfe_i32 v250, v208, 27, 1
	s_nop 0
	v_and_b32_e32 v227, v66, v248
	v_bfe_i32 v249, v230, 26, 1
	v_exp_f32_e32 v66, v81
	s_nop 0
	v_and_b32_e32 v228, v67, v249
	v_exp_f32_e32 v67, v97
	s_nop 1
	v_and_b32_e32 v229, v66, v250
	v_bfe_i32 v251, v230, 27, 1
	v_cvt_pk_bf16_f32 v66, v164, v199
	s_nop 1
	v_and_b32_e32 v230, v67, v251
	v_cvt_pk_bf16_f32 v67, v201, v203
	v_cvt_pk_bf16_f32 v68, v205, v207
	v_cvt_pk_bf16_f32 v69, v210, v212
	v_cvt_pk_bf16_f32 v70, v214, v216
	v_cvt_pk_bf16_f32 v71, v218, v220
	v_cvt_pk_bf16_f32 v72, v223, v225
	v_cvt_pk_bf16_f32 v73, v227, v229
	v_cvt_pk_bf16_f32 v74, v165, v200
	v_cvt_pk_bf16_f32 v75, v202, v204
	v_cvt_pk_bf16_f32 v76, v206, v209
	v_cvt_pk_bf16_f32 v77, v211, v213
	v_cvt_pk_bf16_f32 v78, v215, v217
	v_cvt_pk_bf16_f32 v79, v219, v221
	v_cvt_pk_bf16_f32 v80, v224, v226
	v_cvt_pk_bf16_f32 v81, v228, v230
	s_nop 0
	v_permlane32_swap_b32_e32 v66, v68
	v_permlane32_swap_b32_e32 v67, v69
	v_permlane32_swap_b32_e32 v70, v72
	v_permlane32_swap_b32_e32 v71, v73
	v_permlane32_swap_b32_e32 v74, v76
	v_permlane32_swap_b32_e32 v75, v77
	v_permlane32_swap_b32_e32 v78, v80
	v_permlane32_swap_b32_e32 v79, v81
	ds_read_b64_tr_b16 v[82:83], v168 offset:0
	ds_read_b64_tr_b16 v[84:85], v168 offset:0x800
	ds_read_b64_tr_b16 v[86:87], v168 offset:0x1000
	ds_read_b64_tr_b16 v[88:89], v168 offset:0x1800
	ds_read_b64_tr_b16 v[90:91], v168 offset:0x2000
	ds_read_b64_tr_b16 v[92:93], v168 offset:0x2800
	ds_read_b64_tr_b16 v[94:95], v168 offset:0x3000
	ds_read_b64_tr_b16 v[96:97], v168 offset:0x3800
	s_waitcnt lgkmcnt(0)
	s_nop 0
	v_mfma_f32_32x32x16_bf16 v[48:63], v[66:69], v[82:85], v[48:63]
	ds_read_b64_tr_b16 v[82:83], v168 offset:0x200
	ds_read_b64_tr_b16 v[84:85], v168 offset:0xa00
	v_mfma_f32_32x32x16_bf16 v[48:63], v[70:73], v[86:89], v[48:63]
	ds_read_b64_tr_b16 v[86:87], v168 offset:0x1200
	ds_read_b64_tr_b16 v[88:89], v168 offset:0x1a00
	v_mfma_f32_32x32x16_bf16 v[48:63], v[74:77], v[90:93], v[48:63]
	ds_read_b64_tr_b16 v[90:91], v168 offset:0x2200
	ds_read_b64_tr_b16 v[92:93], v168 offset:0x2a00
	ds_read_b64_tr_b16 v[232:233], v168 offset:0x3200
	ds_read_b64_tr_b16 v[234:235], v168 offset:0x3a00
	s_waitcnt lgkmcnt(0)
	v_mfma_f32_32x32x16_bf16 v[48:63], v[78:81], v[94:97], v[48:63]
	v_mfma_f32_32x32x16_bf16 v[32:47], v[66:69], v[82:85], v[32:47]
	ds_read_b64_tr_b16 v[82:83], v168 offset:0x400
	ds_read_b64_tr_b16 v[84:85], v168 offset:0xc00
	v_mfma_f32_32x32x16_bf16 v[32:47], v[70:73], v[86:89], v[32:47]
	ds_read_b64_tr_b16 v[86:87], v168 offset:0x1400
	ds_read_b64_tr_b16 v[88:89], v168 offset:0x1c00
	v_mfma_f32_32x32x16_bf16 v[32:47], v[74:77], v[90:93], v[32:47]
	ds_read_b64_tr_b16 v[90:91], v168 offset:0x2400
	ds_read_b64_tr_b16 v[92:93], v168 offset:0x2c00
	ds_read_b64_tr_b16 v[94:95], v168 offset:0x3400
	ds_read_b64_tr_b16 v[96:97], v168 offset:0x3c00
	s_waitcnt lgkmcnt(0)
	v_mfma_f32_32x32x16_bf16 v[32:47], v[78:81], v[232:235], v[32:47]
	v_mfma_f32_32x32x16_bf16 v[16:31], v[66:69], v[82:85], v[16:31]
	ds_read_b64_tr_b16 v[82:83], v168 offset:0x600
	ds_read_b64_tr_b16 v[84:85], v168 offset:0xe00
	v_mfma_f32_32x32x16_bf16 v[16:31], v[70:73], v[86:89], v[16:31]
	ds_read_b64_tr_b16 v[86:87], v168 offset:0x1600
	ds_read_b64_tr_b16 v[88:89], v168 offset:0x1e00
	v_mfma_f32_32x32x16_bf16 v[16:31], v[74:77], v[90:93], v[16:31]
	ds_read_b64_tr_b16 v[90:91], v168 offset:0x2600
	ds_read_b64_tr_b16 v[92:93], v168 offset:0x2e00
	ds_read_b64_tr_b16 v[232:233], v168 offset:0x3600
	ds_read_b64_tr_b16 v[234:235], v168 offset:0x3e00
	s_waitcnt lgkmcnt(0)
	v_mfma_f32_32x32x16_bf16 v[16:31], v[78:81], v[94:97], v[16:31]
	v_mfma_f32_32x32x16_bf16 v[0:15], v[66:69], v[82:85], v[0:15]
	s_cmp_gt_u32 s82, s78
	s_waitcnt vmcnt(0)
	s_barrier
	v_mfma_f32_32x32x16_bf16 v[0:15], v[70:73], v[86:89], v[0:15]
	v_mfma_f32_32x32x16_bf16 v[0:15], v[74:77], v[90:93], v[0:15]
	v_mfma_f32_32x32x16_bf16 v[0:15], v[78:81], v[232:235], v[0:15]
	s_cbranch_scc1 .LBB0_1626
	s_mov_b32 m0, s63
	v_lshl_add_u64 v[66:67], v[156:157], 0, s[12:13]
	global_load_lds_dwordx4 v[66:67], off
	v_lshl_add_u64 v[66:67], v[158:159], 0, s[14:15]
	s_mov_b32 m0, s79
	s_nop 0
	global_load_lds_dwordx4 v[66:67], off
	v_lshl_add_u64 v[66:67], v[160:161], 0, s[12:13]
	s_mov_b32 m0, s80
	s_nop 0
	global_load_lds_dwordx4 v[66:67], off
	v_lshl_add_u64 v[66:67], v[162:163], 0, s[14:15]
	s_mov_b32 m0, s81
	s_nop 0
	global_load_lds_dwordx4 v[66:67], off

.LBB0_1628:
	v_add_f32_e32 v158, v164, v165
	v_add_f32_e32 v64, v64, v158
	v_add_f32_e32 v158, v199, v200
	v_add_f32_e32 v64, v64, v158
	v_add_f32_e32 v158, v201, v202
	v_add_f32_e32 v64, v64, v158
	v_add_f32_e32 v158, v203, v204
	v_add_f32_e32 v64, v64, v158
	v_add_f32_e32 v158, v205, v206
	v_add_f32_e32 v64, v64, v158
	v_add_f32_e32 v158, v207, v209
	v_add_f32_e32 v64, v64, v158
	v_add_f32_e32 v158, v210, v211
	v_add_f32_e32 v64, v64, v158
	v_add_f32_e32 v158, v212, v213
	v_add_f32_e32 v64, v64, v158
	v_add_f32_e32 v158, v214, v215
	v_add_f32_e32 v64, v64, v158
	v_add_f32_e32 v158, v216, v217
	v_add_f32_e32 v64, v64, v158
	v_add_f32_e32 v158, v218, v219
	v_add_f32_e32 v64, v64, v158
	v_add_f32_e32 v158, v220, v221
	v_add_f32_e32 v64, v64, v158
	v_add_f32_e32 v158, v223, v224
	v_add_f32_e32 v64, v64, v158
	v_add_f32_e32 v158, v225, v226
	v_add_f32_e32 v64, v64, v158
	v_add_f32_e32 v158, v227, v228
	v_exp_f32_e32 v82, v82
	s_waitcnt lgkmcnt(0)
	v_lshrrev_b32_e32 v156, v180, v156
	v_add_f32_e32 v64, v64, v158
	v_add_f32_e32 v158, v229, v230
	v_add_f32_e32 v64, v64, v158
	v_exp_f32_e32 v66, v66
	v_bfe_i32 v236, v156, 0, 1
	v_lshrrev_b32_e32 v157, v180, v157
	v_exp_f32_e32 v67, v67
	v_exp_f32_e32 v71, v71
	v_and_b32_e32 v158, v82, v236
	v_bfe_i32 v237, v157, 0, 1
	v_bfe_i32 v238, v156, 1, 1
	v_exp_f32_e32 v73, v73
	v_and_b32_e32 v159, v66, v237
	v_add_f32_e32 v66, v158, v159
	v_add_f32_e32 v64, v64, v66
	v_exp_f32_e32 v66, v83
	v_bfe_i32 v246, v157, 9, 1
	v_exp_f32_e32 v75, v75
	v_and_b32_e32 v160, v66, v238
	v_bfe_i32 v239, v157, 1, 1
	v_exp_f32_e32 v77, v77
	v_exp_f32_e32 v79, v79
	v_and_b32_e32 v161, v67, v239
	v_add_f32_e32 v66, v160, v161
	v_add_f32_e32 v64, v64, v66
	v_exp_f32_e32 v66, v84
	v_exp_f32_e32 v67, v68
	v_bfe_i32 v240, v156, 2, 1
	v_bfe_i32 v242, v156, 3, 1
	v_bfe_i32 v247, v157, 8, 1
	v_and_b32_e32 v162, v66, v240
	v_bfe_i32 v241, v157, 2, 1
	v_exp_f32_e32 v81, v81
	s_nop 0
	v_and_b32_e32 v163, v67, v241
	v_add_f32_e32 v66, v162, v163
	v_add_f32_e32 v64, v64, v66
	v_exp_f32_e32 v66, v85
	v_exp_f32_e32 v67, v69
	v_exp_f32_e32 v69, v87
	v_bfe_i32 v244, v156, 9, 1
	v_and_b32_e32 v164, v66, v242
	v_bfe_i32 v243, v157, 3, 1
	s_nop 1
	v_and_b32_e32 v165, v67, v243
	v_add_f32_e32 v66, v164, v165
	v_add_f32_e32 v64, v64, v66
	v_exp_f32_e32 v66, v86
	v_exp_f32_e32 v67, v70
	v_bfe_i32 v245, v156, 8, 1
	v_bfe_i32 v251, v157, 10, 1
	s_nop 0
	v_and_b32_e32 v69, v69, v244
	v_bfe_i32 v248, v156, 11, 1
	s_nop 0
	v_and_b32_e32 v68, v66, v245
	s_nop 1
	v_and_b32_e32 v83, v71, v246
	v_exp_f32_e32 v71, v89
	v_bfe_i32 v250, v157, 11, 1
	v_and_b32_e32 v82, v67, v247
	v_pk_add_f32 v[66:67], v[68:69], v[82:83]
	v_add_f32_e32 v64, v64, v66
	v_exp_f32_e32 v66, v88
	v_add_f32_e32 v64, v64, v67
	v_exp_f32_e32 v67, v72
	v_bfe_i32 v249, v156, 10, 1
	v_and_b32_e32 v71, v71, v248
	v_bfe_i32 v236, v156, 17, 1
	v_bfe_i32 v239, v157, 16, 1
	v_and_b32_e32 v70, v66, v249
	s_nop 1
	v_and_b32_e32 v85, v73, v250
	v_exp_f32_e32 v73, v91
	v_bfe_i32 v238, v157, 17, 1
	v_and_b32_e32 v84, v67, v251
	v_pk_add_f32 v[66:67], v[70:71], v[84:85]
	v_add_f32_e32 v64, v64, v66
	v_exp_f32_e32 v66, v90
	v_add_f32_e32 v64, v64, v67
	v_exp_f32_e32 v67, v74
	v_bfe_i32 v237, v156, 16, 1
	v_and_b32_e32 v73, v73, v236
	v_bfe_i32 v240, v156, 19, 1
	v_bfe_i32 v243, v157, 18, 1
	v_and_b32_e32 v72, v66, v237
	s_nop 1
	v_and_b32_e32 v87, v75, v238
	v_exp_f32_e32 v75, v93
	v_bfe_i32 v242, v157, 19, 1
	v_and_b32_e32 v86, v67, v239
	v_pk_add_f32 v[66:67], v[72:73], v[86:87]
	v_add_f32_e32 v64, v64, v66
	v_exp_f32_e32 v66, v92
	v_add_f32_e32 v64, v64, v67
	v_exp_f32_e32 v67, v76
	v_bfe_i32 v241, v156, 18, 1
	v_and_b32_e32 v75, v75, v240
	v_bfe_i32 v244, v156, 25, 1
	v_bfe_i32 v247, v157, 24, 1
	v_and_b32_e32 v74, v66, v241
	s_nop 1
	v_and_b32_e32 v89, v77, v242
	v_exp_f32_e32 v77, v95
	v_bfe_i32 v246, v157, 25, 1
	v_and_b32_e32 v88, v67, v243
	v_pk_add_f32 v[66:67], v[74:75], v[88:89]
	v_add_f32_e32 v64, v64, v66
	v_exp_f32_e32 v66, v94
	v_add_f32_e32 v64, v64, v67
	v_exp_f32_e32 v67, v78
	v_bfe_i32 v245, v156, 24, 1
	v_and_b32_e32 v77, v77, v244
	v_bfe_i32 v248, v156, 27, 1
	v_bfe_i32 v251, v157, 26, 1
	v_and_b32_e32 v76, v66, v245
	s_nop 1
	v_and_b32_e32 v91, v79, v246
	v_exp_f32_e32 v79, v97
	v_bfe_i32 v250, v157, 27, 1
	v_and_b32_e32 v90, v67, v247
	v_pk_add_f32 v[66:67], v[76:77], v[90:91]
	v_add_f32_e32 v64, v64, v66
	v_exp_f32_e32 v66, v96
	v_add_f32_e32 v64, v64, v67
	v_exp_f32_e32 v67, v80
	v_bfe_i32 v249, v156, 26, 1
	v_and_b32_e32 v79, v79, v248
	s_nop 1
	v_and_b32_e32 v78, v66, v249
	s_nop 1
	v_and_b32_e32 v93, v81, v250
	s_nop 1
	v_and_b32_e32 v92, v67, v251
	v_pk_add_f32 v[66:67], v[78:79], v[92:93]
	s_nop 0
	v_add_f32_e32 v64, v64, v66
	v_add_f32_e32 v64, v64, v67
	v_cvt_pk_bf16_f32 v66, v158, v160
	v_cvt_pk_bf16_f32 v67, v162, v164
	v_cvt_pk_bf16_f32 v68, v68, v69
	v_cvt_pk_bf16_f32 v69, v70, v71
	v_cvt_pk_bf16_f32 v70, v72, v73
	v_cvt_pk_bf16_f32 v71, v74, v75
	v_cvt_pk_bf16_f32 v72, v76, v77
	v_cvt_pk_bf16_f32 v73, v78, v79
	v_cvt_pk_bf16_f32 v74, v159, v161
	v_cvt_pk_bf16_f32 v75, v163, v165
	v_cvt_pk_bf16_f32 v76, v82, v83
	v_cvt_pk_bf16_f32 v77, v84, v85
	v_cvt_pk_bf16_f32 v78, v86, v87
	v_cvt_pk_bf16_f32 v79, v88, v89
	v_cvt_pk_bf16_f32 v80, v90, v91
	v_cvt_pk_bf16_f32 v81, v92, v93
	s_nop 0
	v_permlane32_swap_b32_e32 v66, v68
	v_permlane32_swap_b32_e32 v67, v69
	v_permlane32_swap_b32_e32 v70, v72
	v_permlane32_swap_b32_e32 v71, v73
	v_permlane32_swap_b32_e32 v74, v76
	v_permlane32_swap_b32_e32 v75, v77
	v_permlane32_swap_b32_e32 v78, v80
	v_permlane32_swap_b32_e32 v79, v81
	ds_read_b64_tr_b16 v[82:83], v181 offset:0
	ds_read_b64_tr_b16 v[84:85], v181 offset:0x800
	ds_read_b64_tr_b16 v[86:87], v181 offset:0x1000
	ds_read_b64_tr_b16 v[88:89], v181 offset:0x1800
	ds_read_b64_tr_b16 v[90:91], v181 offset:0x2000
	ds_read_b64_tr_b16 v[92:93], v181 offset:0x2800
	ds_read_b64_tr_b16 v[94:95], v181 offset:0x3000
	ds_read_b64_tr_b16 v[96:97], v181 offset:0x3800
	s_waitcnt lgkmcnt(0)
	s_nop 0
	v_mfma_f32_32x32x16_bf16 v[48:63], v[66:69], v[82:85], v[48:63]
	ds_read_b64_tr_b16 v[82:83], v181 offset:0x200
	ds_read_b64_tr_b16 v[84:85], v181 offset:0xa00
	v_mfma_f32_32x32x16_bf16 v[48:63], v[70:73], v[86:89], v[48:63]
	ds_read_b64_tr_b16 v[86:87], v181 offset:0x1200
	ds_read_b64_tr_b16 v[88:89], v181 offset:0x1a00
	v_mfma_f32_32x32x16_bf16 v[48:63], v[74:77], v[90:93], v[48:63]
	ds_read_b64_tr_b16 v[90:91], v181 offset:0x2200
	ds_read_b64_tr_b16 v[92:93], v181 offset:0x2a00
	ds_read_b64_tr_b16 v[156:157], v181 offset:0x3200
	ds_read_b64_tr_b16 v[158:159], v181 offset:0x3a00
	s_waitcnt lgkmcnt(0)
	v_mfma_f32_32x32x16_bf16 v[48:63], v[78:81], v[94:97], v[48:63]
	v_mfma_f32_32x32x16_bf16 v[32:47], v[66:69], v[82:85], v[32:47]
	ds_read_b64_tr_b16 v[82:83], v181 offset:0x400
	ds_read_b64_tr_b16 v[84:85], v181 offset:0xc00
	v_mfma_f32_32x32x16_bf16 v[32:47], v[70:73], v[86:89], v[32:47]
	ds_read_b64_tr_b16 v[86:87], v181 offset:0x1400
	ds_read_b64_tr_b16 v[88:89], v181 offset:0x1c00
	v_mfma_f32_32x32x16_bf16 v[32:47], v[74:77], v[90:93], v[32:47]
	ds_read_b64_tr_b16 v[90:91], v181 offset:0x2400
	ds_read_b64_tr_b16 v[92:93], v181 offset:0x2c00
	ds_read_b64_tr_b16 v[94:95], v181 offset:0x3400
	ds_read_b64_tr_b16 v[96:97], v181 offset:0x3c00
	s_waitcnt lgkmcnt(0)
	v_mfma_f32_32x32x16_bf16 v[32:47], v[78:81], v[156:159], v[32:47]
	v_mfma_f32_32x32x16_bf16 v[16:31], v[66:69], v[82:85], v[16:31]
	ds_read_b64_tr_b16 v[82:83], v181 offset:0x600
	ds_read_b64_tr_b16 v[84:85], v181 offset:0xe00
	v_mfma_f32_32x32x16_bf16 v[16:31], v[70:73], v[86:89], v[16:31]
	ds_read_b64_tr_b16 v[86:87], v181 offset:0x1600
	ds_read_b64_tr_b16 v[88:89], v181 offset:0x1e00
	v_mfma_f32_32x32x16_bf16 v[16:31], v[74:77], v[90:93], v[16:31]
	ds_read_b64_tr_b16 v[90:91], v181 offset:0x2600
	ds_read_b64_tr_b16 v[92:93], v181 offset:0x2e00
	ds_read_b64_tr_b16 v[156:157], v181 offset:0x3600
	ds_read_b64_tr_b16 v[158:159], v181 offset:0x3e00
	s_waitcnt lgkmcnt(0)
	v_mfma_f32_32x32x16_bf16 v[16:31], v[78:81], v[94:97], v[16:31]
	v_mfma_f32_32x32x16_bf16 v[0:15], v[66:69], v[82:85], v[0:15]
	s_add_i32 s84, s82, 2
	s_add_u32 s0, s0, 0x20000
	s_addc_u32 s1, s1, 0
	v_add_u32_e32 v65, 0xfffffe00, v65
	v_add_u32_e32 v188, 0xfffffe00, v188
	v_add_u32_e32 v189, 16, v189
	s_cmp_lt_u32 s82, s78
	v_mfma_f32_32x32x16_bf16 v[0:15], v[70:73], v[86:89], v[0:15]
	s_waitcnt vmcnt(0)
	s_barrier
	v_mfma_f32_32x32x16_bf16 v[0:15], v[74:77], v[90:93], v[0:15]
	v_mfma_f32_32x32x16_bf16 v[0:15], v[78:81], v[156:159], v[0:15]
	s_cbranch_scc0 .LBB0_1631
	s_mov_b32 s82, s84
	s_branch .LBB0_1622

.LBB0_1631:
	s_xor_b64 s[0:1], s[48:49], -1
	s_cmp_gt_u32 s82, s78
	s_cbranch_scc1 .LBB0_1633
	v_add_u32_e32 v65, v171, v172
	ds_read_b128 v[66:69], v65 offset:32768
	ds_read_b128 v[82:85], v65 offset:40960
	v_add_u32_e32 v65, v171, v173
	s_waitcnt lgkmcnt(1)
	v_mfma_f32_32x32x16_f16 v[66:81], v[66:69], v[106:109], 0
	s_waitcnt lgkmcnt(0)
	v_mfma_f32_32x32x16_f16 v[82:97], v[82:85], v[106:109], 0
	ds_read_b128 v[106:109], v65 offset:32768
	ds_read_b128 v[156:159], v65 offset:40960
	v_add_u32_e32 v65, v171, v174
	s_waitcnt lgkmcnt(1)
	v_mfma_f32_32x32x16_f16 v[66:81], v[106:109], v[98:101], v[66:81]
	s_waitcnt lgkmcnt(0)
	v_mfma_f32_32x32x16_f16 v[82:97], v[156:159], v[98:101], v[82:97]
	ds_read_b128 v[98:101], v65 offset:32768
	ds_read_b128 v[106:109], v65 offset:40960
	v_add_u32_e32 v65, v171, v175
	s_waitcnt lgkmcnt(1)
	v_mfma_f32_32x32x16_f16 v[66:81], v[98:101], v[102:105], v[66:81]
	s_waitcnt lgkmcnt(0)
	v_mfma_f32_32x32x16_f16 v[82:97], v[106:109], v[102:105], v[82:97]
	ds_read_b128 v[98:101], v65 offset:32768
	ds_read_b128 v[102:105], v65 offset:40960
	v_add_u32_e32 v65, v171, v176
	s_waitcnt lgkmcnt(1)
	v_mfma_f32_32x32x16_f16 v[66:81], v[98:101], v[110:113], v[66:81]
	s_waitcnt lgkmcnt(0)
	v_mfma_f32_32x32x16_f16 v[82:97], v[102:105], v[110:113], v[82:97]
	ds_read_b128 v[98:101], v65 offset:32768
	ds_read_b128 v[102:105], v65 offset:40960
	v_add_u32_e32 v65, v171, v177
	v_lshl_add_u32 v112, s82, 3, v170
	s_waitcnt lgkmcnt(1)
	v_mfma_f32_32x32x16_f16 v[66:81], v[98:101], v[118:121], v[66:81]
	s_waitcnt lgkmcnt(0)
	v_mfma_f32_32x32x16_f16 v[82:97], v[102:105], v[118:121], v[82:97]
	ds_read_b128 v[98:101], v65 offset:32768
	ds_read_b128 v[102:105], v65 offset:40960
	v_add_u32_e32 v65, v171, v178
	s_waitcnt lgkmcnt(1)
	v_mfma_f32_32x32x16_f16 v[66:81], v[98:101], v[122:125], v[66:81]
	s_waitcnt lgkmcnt(0)
	v_mfma_f32_32x32x16_f16 v[82:97], v[102:105], v[122:125], v[82:97]
	ds_read_b128 v[98:101], v65 offset:32768
	ds_read_b128 v[102:105], v65 offset:40960
	v_add_u32_e32 v65, v171, v179
	s_waitcnt lgkmcnt(1)
	v_mfma_f32_32x32x16_f16 v[66:81], v[98:101], v[126:129], v[66:81]
	s_waitcnt lgkmcnt(0)
	v_mfma_f32_32x32x16_f16 v[82:97], v[102:105], v[126:129], v[82:97]
	ds_read_b128 v[98:101], v65 offset:32768
	ds_read_b128 v[102:105], v65 offset:40960
	v_lshl_or_b32 v65, s82, 6, v180
	v_sub_u32_e32 v65, v138, v65
	v_lshl_add_u32 v65, v65, 2, s55
	s_waitcnt lgkmcnt(1)
	v_mfma_f32_32x32x16_f16 v[66:81], v[98:101], v[114:117], v[66:81]
	ds_read2_b32 v[98:99], v65 offset0:63 offset1:64
	ds_read2_b32 v[100:101], v65 offset0:31 offset1:32
	ds_read2_b32 v[106:107], v65 offset0:45 offset1:46
	ds_read2_b32 v[108:109], v65 offset0:39 offset1:40
	ds_read2_b32 v[110:111], v65 offset0:37 offset1:38
	s_waitcnt lgkmcnt(4)
	s_nop 5
	v_add_f32_e32 v113, v66, v99
	v_mfma_f32_32x32x16_f16 v[82:97], v[102:105], v[114:117], v[82:97]
	v_add_f32_e32 v104, v67, v98
	ds_read2_b32 v[66:67], v65 offset0:29 offset1:30
	ds_read2_b32 v[102:103], v65 offset0:61 offset1:62
	s_waitcnt lgkmcnt(5)
	s_nop 7
	v_add_f32_e32 v101, v82, v101
	v_add_f32_e32 v100, v83, v100
	ds_read2_b32 v[82:83], v65 offset0:55 offset1:56
	ds_read2_b32 v[98:99], v65 offset0:23 offset1:24
	s_waitcnt lgkmcnt(3)
	v_add_f32_e32 v84, v84, v67
	v_add_f32_e32 v85, v85, v66
	ds_read2_b32 v[66:67], v65 offset0:53 offset1:54
	s_waitcnt lgkmcnt(3)
	v_add_f32_e32 v103, v68, v103
	v_add_f32_e32 v102, v69, v102
	s_waitcnt lgkmcnt(2)
	v_add_f32_e32 v105, v70, v83
	ds_read2_b32 v[68:69], v65 offset0:21 offset1:22
	s_waitcnt lgkmcnt(2)
	v_add_f32_e32 v86, v86, v99
	v_add_f32_e32 v99, v71, v82
	ds_read2_b32 v[70:71], v65 offset0:47 offset1:48
	s_waitcnt lgkmcnt(2)
	v_add_f32_e32 v72, v72, v67
	ds_read2_b32 v[82:83], v65 offset0:15 offset1:16
	v_add_f32_e32 v73, v73, v66
	ds_read2_b32 v[66:67], v65 offset0:13 offset1:14
	s_waitcnt lgkmcnt(3)
	v_add_f32_e32 v88, v88, v69
	v_add_f32_e32 v89, v89, v68
	s_waitcnt lgkmcnt(2)
	v_add_f32_e32 v74, v74, v71
	v_add_f32_e32 v75, v75, v70
	s_waitcnt lgkmcnt(1)
	v_add_f32_e32 v82, v91, v82
	ds_read2_b32 v[68:69], v65 offset0:7 offset1:8
	s_waitcnt lgkmcnt(1)
	v_add_f32_e32 v91, v92, v67
	v_add_f32_e32 v93, v93, v66
	ds_read_b64 v[66:67], v112
	ds_read2_b32 v[70:71], v65 offset0:5 offset1:6
	v_exp_f32_e32 v65, v113
	s_waitcnt lgkmcnt(2)
	v_add_f32_e32 v94, v94, v69
	v_add_f32_e32 v95, v95, v68
	s_waitcnt lgkmcnt(1)
	v_lshrrev_b32_e32 v66, v180, v66
	v_exp_f32_e32 v68, v101
	v_bfe_i32 v236, v66, 0, 1
	v_lshrrev_b32_e32 v67, v180, v67
	v_add_f32_e32 v87, v87, v98
	v_add_f32_e32 v98, v78, v109
	v_and_b32_e32 v101, v65, v236
	v_bfe_i32 v237, v67, 0, 1
	v_bfe_i32 v238, v66, 1, 1
	v_add_f32_e32 v92, v77, v106
	v_and_b32_e32 v109, v68, v237
	v_add_f32_e32 v65, v101, v109
	v_add_f32_e32 v64, v64, v65
	v_exp_f32_e32 v65, v104
	v_exp_f32_e32 v68, v100
	v_bfe_i32 v240, v66, 2, 1
	v_add_f32_e32 v106, v79, v108
	v_and_b32_e32 v100, v65, v238
	v_bfe_i32 v239, v67, 1, 1
	v_add_f32_e32 v108, v81, v110
	v_add_f32_e32 v83, v90, v83
	v_and_b32_e32 v104, v68, v239
	v_add_f32_e32 v65, v100, v104
	v_add_f32_e32 v64, v64, v65
	v_exp_f32_e32 v65, v103
	v_exp_f32_e32 v68, v84
	v_bfe_i32 v242, v66, 3, 1
	v_add_f32_e32 v90, v76, v107
	v_and_b32_e32 v103, v65, v240
	v_bfe_i32 v241, v67, 2, 1
	v_add_f32_e32 v107, v80, v111
	s_waitcnt lgkmcnt(0)
	v_add_f32_e32 v97, v97, v70
	v_and_b32_e32 v110, v68, v241
	v_add_f32_e32 v65, v103, v110
	v_add_f32_e32 v64, v64, v65
	v_exp_f32_e32 v65, v102
	v_exp_f32_e32 v68, v85
	v_bfe_i32 v244, v66, 9, 1
	v_add_f32_e32 v96, v96, v71
	v_and_b32_e32 v102, v65, v242
	v_bfe_i32 v243, v67, 3, 1
	v_exp_f32_e32 v71, v87
	v_bfe_i32 v245, v66, 8, 1
	v_and_b32_e32 v111, v68, v243
	v_add_f32_e32 v65, v102, v111
	v_exp_f32_e32 v68, v99
	v_add_f32_e32 v70, v64, v65
	v_exp_f32_e32 v64, v105
	v_exp_f32_e32 v65, v86
	v_bfe_i32 v243, v67, 18, 1
	v_and_b32_e32 v69, v68, v244
	v_bfe_i32 v247, v67, 8, 1
	v_exp_f32_e32 v86, v95
	v_and_b32_e32 v68, v64, v245
	v_bfe_i32 v246, v67, 9, 1
	v_bfe_i32 v245, v66, 24, 1
	s_nop 0
	v_and_b32_e32 v77, v71, v246
	v_bfe_i32 v248, v66, 11, 1
	s_nop 0
	v_and_b32_e32 v76, v65, v247
	v_pk_add_f32 v[64:65], v[68:69], v[76:77]
	v_add_f32_e32 v64, v70, v64
	v_exp_f32_e32 v70, v73
	v_add_f32_e32 v80, v64, v65
	v_exp_f32_e32 v64, v72
	v_exp_f32_e32 v72, v89
	v_bfe_i32 v249, v66, 10, 1
	v_exp_f32_e32 v65, v88
	v_and_b32_e32 v71, v70, v248
	v_bfe_i32 v251, v67, 10, 1
	v_bfe_i32 v247, v67, 24, 1
	v_and_b32_e32 v70, v64, v249
	v_bfe_i32 v250, v67, 11, 1
	s_nop 1
	v_and_b32_e32 v79, v72, v250
	v_exp_f32_e32 v72, v75
	v_bfe_i32 v236, v66, 17, 1
	v_and_b32_e32 v78, v65, v251
	v_pk_add_f32 v[64:65], v[70:71], v[78:79]
	v_bfe_i32 v237, v66, 16, 1
	v_add_f32_e32 v64, v80, v64
	v_add_f32_e32 v84, v64, v65
	v_exp_f32_e32 v64, v74
	v_exp_f32_e32 v74, v82
	v_exp_f32_e32 v65, v83
	v_exp_f32_e32 v82, v93
	v_and_b32_e32 v73, v72, v236
	v_bfe_i32 v239, v67, 16, 1
	v_bfe_i32 v241, v66, 18, 1
	v_and_b32_e32 v72, v64, v237
	v_bfe_i32 v238, v67, 17, 1
	s_nop 1
	v_and_b32_e32 v81, v74, v238
	v_exp_f32_e32 v74, v92
	v_bfe_i32 v240, v66, 19, 1
	v_and_b32_e32 v80, v65, v239
	v_pk_add_f32 v[64:65], v[72:73], v[80:81]
	v_add_f32_e32 v64, v84, v64
	v_add_f32_e32 v84, v64, v65
	v_exp_f32_e32 v64, v90
	v_exp_f32_e32 v65, v91
	v_and_b32_e32 v75, v74, v240
	v_exp_f32_e32 v90, v97
	s_nop 0
	v_and_b32_e32 v74, v64, v241
	v_bfe_i32 v242, v67, 19, 1
	s_nop 1
	v_and_b32_e32 v83, v82, v242
	v_bfe_i32 v244, v66, 25, 1
	s_nop 0
	v_and_b32_e32 v82, v65, v243
	v_pk_add_f32 v[64:65], v[74:75], v[82:83]
	v_add_f32_e32 v64, v84, v64
	v_exp_f32_e32 v84, v106
	v_add_f32_e32 v88, v64, v65
	v_exp_f32_e32 v64, v98
	v_exp_f32_e32 v65, v94
	v_and_b32_e32 v85, v84, v244
	s_nop 1
	v_and_b32_e32 v84, v64, v245
	v_bfe_i32 v246, v67, 25, 1
	s_nop 1
	v_and_b32_e32 v87, v86, v246
	v_bfe_i32 v248, v66, 27, 1
	v_bfe_i32 v249, v66, 26, 1
	v_and_b32_e32 v86, v65, v247
	v_pk_add_f32 v[64:65], v[84:85], v[86:87]
	v_add_f32_e32 v64, v88, v64
	v_exp_f32_e32 v88, v108
	v_add_f32_e32 v92, v64, v65
	v_exp_f32_e32 v64, v107
	v_exp_f32_e32 v65, v96
	v_and_b32_e32 v89, v88, v248
	v_bfe_i32 v251, v67, 26, 1
	s_nop 0
	v_and_b32_e32 v88, v64, v249
	v_bfe_i32 v250, v67, 27, 1
	s_nop 1
	v_and_b32_e32 v91, v90, v250
	v_cvt_pk_bf16_f32 v66, v101, v100
	v_cvt_pk_bf16_f32 v67, v103, v102
	v_cvt_pk_bf16_f32 v68, v68, v69
	v_cvt_pk_bf16_f32 v69, v70, v71
	v_cvt_pk_bf16_f32 v70, v72, v73
	s_nop 1
	v_and_b32_e32 v90, v65, v251
	v_pk_add_f32 v[64:65], v[88:89], v[90:91]
	v_cvt_pk_bf16_f32 v71, v74, v75
	v_cvt_pk_bf16_f32 v72, v84, v85
	v_cvt_pk_bf16_f32 v73, v88, v89
	v_cvt_pk_bf16_f32 v74, v109, v104
	v_cvt_pk_bf16_f32 v75, v110, v111
	s_nop 0
	v_add_f32_e32 v64, v92, v64
	v_add_f32_e32 v64, v64, v65
	v_cvt_pk_bf16_f32 v76, v76, v77
	v_cvt_pk_bf16_f32 v77, v78, v79
	v_cvt_pk_bf16_f32 v78, v80, v81
	v_cvt_pk_bf16_f32 v79, v82, v83
	v_cvt_pk_bf16_f32 v80, v86, v87
	v_cvt_pk_bf16_f32 v81, v90, v91
	v_permlane32_swap_b32_e32 v66, v68
	v_permlane32_swap_b32_e32 v67, v69
	v_permlane32_swap_b32_e32 v70, v72
	v_permlane32_swap_b32_e32 v71, v73
	v_permlane32_swap_b32_e32 v74, v76
	v_permlane32_swap_b32_e32 v75, v77
	v_permlane32_swap_b32_e32 v78, v80
	v_permlane32_swap_b32_e32 v79, v81
	ds_read_b64_tr_b16 v[82:83], v168 offset:0
	ds_read_b64_tr_b16 v[84:85], v168 offset:0x800
	ds_read_b64_tr_b16 v[86:87], v168 offset:0x1000
	ds_read_b64_tr_b16 v[88:89], v168 offset:0x1800
	ds_read_b64_tr_b16 v[90:91], v168 offset:0x2000
	ds_read_b64_tr_b16 v[92:93], v168 offset:0x2800
	ds_read_b64_tr_b16 v[94:95], v168 offset:0x3000
	ds_read_b64_tr_b16 v[96:97], v168 offset:0x3800
	s_waitcnt lgkmcnt(0)
	s_nop 0
	v_mfma_f32_32x32x16_bf16 v[48:63], v[66:69], v[82:85], v[48:63]
	ds_read_b64_tr_b16 v[82:83], v168 offset:0x200
	ds_read_b64_tr_b16 v[84:85], v168 offset:0xa00
	v_mfma_f32_32x32x16_bf16 v[48:63], v[70:73], v[86:89], v[48:63]
	ds_read_b64_tr_b16 v[86:87], v168 offset:0x1200
	ds_read_b64_tr_b16 v[88:89], v168 offset:0x1a00
	v_mfma_f32_32x32x16_bf16 v[48:63], v[74:77], v[90:93], v[48:63]
	ds_read_b64_tr_b16 v[90:91], v168 offset:0x2200
	ds_read_b64_tr_b16 v[92:93], v168 offset:0x2a00
	ds_read_b64_tr_b16 v[98:99], v168 offset:0x3200
	ds_read_b64_tr_b16 v[100:101], v168 offset:0x3a00
	s_waitcnt lgkmcnt(0)
	v_mfma_f32_32x32x16_bf16 v[48:63], v[78:81], v[94:97], v[48:63]
	v_mfma_f32_32x32x16_bf16 v[32:47], v[66:69], v[82:85], v[32:47]
	ds_read_b64_tr_b16 v[82:83], v168 offset:0x400
	ds_read_b64_tr_b16 v[84:85], v168 offset:0xc00
	v_mfma_f32_32x32x16_bf16 v[32:47], v[70:73], v[86:89], v[32:47]
	ds_read_b64_tr_b16 v[86:87], v168 offset:0x1400
	ds_read_b64_tr_b16 v[88:89], v168 offset:0x1c00
	v_mfma_f32_32x32x16_bf16 v[32:47], v[74:77], v[90:93], v[32:47]
	ds_read_b64_tr_b16 v[90:91], v168 offset:0x2400
	ds_read_b64_tr_b16 v[92:93], v168 offset:0x2c00
	ds_read_b64_tr_b16 v[94:95], v168 offset:0x3400
	ds_read_b64_tr_b16 v[96:97], v168 offset:0x3c00
	s_waitcnt lgkmcnt(0)
	v_mfma_f32_32x32x16_bf16 v[32:47], v[78:81], v[98:101], v[32:47]
	v_mfma_f32_32x32x16_bf16 v[16:31], v[66:69], v[82:85], v[16:31]
	ds_read_b64_tr_b16 v[82:83], v168 offset:0x600
	ds_read_b64_tr_b16 v[84:85], v168 offset:0xe00
	v_mfma_f32_32x32x16_bf16 v[16:31], v[70:73], v[86:89], v[16:31]
	ds_read_b64_tr_b16 v[86:87], v168 offset:0x1600
	ds_read_b64_tr_b16 v[88:89], v168 offset:0x1e00
	v_mfma_f32_32x32x16_bf16 v[16:31], v[74:77], v[90:93], v[16:31]
	ds_read_b64_tr_b16 v[90:91], v168 offset:0x2600
	ds_read_b64_tr_b16 v[92:93], v168 offset:0x2e00
	ds_read_b64_tr_b16 v[98:99], v168 offset:0x3600
	ds_read_b64_tr_b16 v[100:101], v168 offset:0x3e00
	s_waitcnt lgkmcnt(0)
	v_mfma_f32_32x32x16_bf16 v[16:31], v[78:81], v[94:97], v[16:31]
	v_mfma_f32_32x32x16_bf16 v[0:15], v[66:69], v[82:85], v[0:15]
	s_barrier
	v_mfma_f32_32x32x16_bf16 v[0:15], v[70:73], v[86:89], v[0:15]
	v_mfma_f32_32x32x16_bf16 v[0:15], v[74:77], v[90:93], v[0:15]
	v_mfma_f32_32x32x16_bf16 v[0:15], v[78:81], v[98:101], v[0:15]
